# MLA attention: second 64-key block's first 8 K fragments prefetched from LDS during the first block's softmax (new registers v214-v245), counted lgkmcnt
# baseline (speedup 1.0000x reference)
; #define LAS __attribute__((address_space(3)))
; #define MFMA32(a, b, c) __builtin_amdgcn_mfma_f32_32x32x16_bf16((a), (b), (c), 0, 0, 0)
; template <int DQK, int DV, bool CAUSAL, int KT, bool PRIO>
; DI void attn_unit(const bf16_t* Qb, int qpitch, const bf16_t* Kb, int kpitch, const bf16_t* Vtb, int vpitch, bf16_t* Ob, int opitch, int q0, int nt, LAS unsigned char* lds, float kbound, const float* qgain, const int* qpos, float qscale) {
;     ...
;                     constexpr int KSN = DQK / 16, NDB = DV / 32;
;                     f32x16 s0 = negm, s1 = negm;
;                     const LAS unsigned char* kb = lds + buf * KBUF + (64 * hf + r) * KS + h * 16;
;                     const LAS unsigned char* vb = lds + VOFF + buf * VBUF + r * VS + h * 8 + 128 * hf;
;                     bf16x8 kf0[KSN], kf1[KSN], vf[4][NDB];
; #pragma unroll
;                     for (int ks = 0; ks < KSN; ++ks) { kf0[ks] = *(const LAS bf16x8*)(kb + ks * 32); kf1[ks] = *(const LAS bf16x8*)(kb + 32 * KS + ks * 32); }
;                     __builtin_amdgcn_sched_barrier(0); __builtin_amdgcn_s_setprio(1); __builtin_amdgcn_sched_barrier(0);
; #pragma unroll
;                     for (int ks = 0; ks < KSN; ++ks) { s0 = MFMA32(kf0[ks], qf[ks], s0); s1 = MFMA32(kf1[ks], qf[ks], s1); }
;                     __builtin_amdgcn_sched_barrier(0); __builtin_amdgcn_s_setprio(0); __builtin_amdgcn_sched_barrier(0);
; #pragma unroll
;                     for (int q4 = 0; q4 < 4; ++q4)
; #pragma unroll
;                         for (int d = 0; d < NDB; ++d) { const LAS unsigned char* vp = vb + d * 32 * VS + q4 * 32;
;                             const s16x4 lo = *(const LAS s16x4*)vp, hi = *(const LAS s16x4*)(vp + 16); vf[q4][d] = (bf16x8){lo[0], lo[1], lo[2], lo[3], hi[0], hi[1], hi[2], hi[3]}; }
;                     if (CAUSAL && key0 + 63 > qlo) {
; #pragma unroll
;                         for (int i = 0; i < 16; ++i) { const int key = key0 + (i & 3) + 8 * (i >> 2) + 4 * h; if (key > qabs) s0[i] = -1e30f; if (key + 32 > qabs) s1[i] = -1e30f; }
.Lmla_b1_pre:
	ds_read_b128 v[214:217], v194 offset:13312
	ds_read_b128 v[218:221], v194 offset:13344
	ds_read_b128 v[222:225], v194 offset:19968
	ds_read_b128 v[226:229], v194 offset:20000
	ds_read_b128 v[230:233], v194 offset:13376
	ds_read_b128 v[234:237], v194 offset:13408
	ds_read_b128 v[238:241], v194 offset:20032
	ds_read_b128 v[242:245], v194 offset:20064
	s_branch .LBB0_1505
.LBB0_1495:
	ds_read_b128 v[2:5], v194
	ds_read_b128 v[6:9], v194 offset:32
	ds_read_b128 v[10:13], v194 offset:6656
	ds_read_b128 v[140:143], v194 offset:6688
	ds_read_b128 v[144:147], v194 offset:64
	ds_read_b128 v[148:151], v194 offset:96
	ds_read_b128 v[152:155], v194 offset:6720
	ds_read_b128 v[156:159], v194 offset:6752
	ds_read_b128 v[198:201], v194 offset:128
	ds_read_b128 v[202:205], v194 offset:160
	ds_read_b128 v[206:209], v194 offset:6784
	ds_read_b128 v[210:213], v194 offset:6816
	s_setprio 1
	s_setprio 0
	s_waitcnt lgkmcnt(0)
	v_mfma_f32_32x32x16_bf16 v[80:95], v[2:5], v[116:119], v[48:63]
	s_cmp_le_i32 s71, s69
	v_mfma_f32_32x32x16_bf16 v[64:79], v[10:13], v[116:119], v[48:63]
	v_mfma_f32_32x32x16_bf16 v[80:95], v[6:9], v[120:123], v[80:95]
	v_mfma_f32_32x32x16_bf16 v[64:79], v[140:143], v[120:123], v[64:79]
	v_mfma_f32_32x32x16_bf16 v[80:95], v[144:147], v[124:127], v[80:95]
	v_mfma_f32_32x32x16_bf16 v[64:79], v[152:155], v[124:127], v[64:79]
	ds_read2_b64 v[152:155], v14 offset1:2
	ds_read2_b64 v[140:143], v14 offset0:4 offset1:6
	v_mfma_f32_32x32x16_bf16 v[80:95], v[148:151], v[128:131], v[80:95]
	v_mfma_f32_32x32x16_bf16 v[64:79], v[156:159], v[128:131], v[64:79]
	ds_read2_b64 v[156:159], v15 offset0:32 offset1:34
	ds_read2_b64 v[148:151], v15 offset0:36 offset1:38
	ds_read2_b64 v[144:147], v14 offset0:8 offset1:10
	ds_read2_b64 v[10:13], v15 offset0:40 offset1:42
	ds_read2_b64 v[6:9], v14 offset0:12 offset1:14
	ds_read2_b64 v[2:5], v15 offset0:44 offset1:46
	v_mfma_f32_32x32x16_bf16 v[80:95], v[198:201], v[132:135], v[80:95]
	v_mfma_f32_32x32x16_bf16 v[64:79], v[206:209], v[132:135], v[64:79]
	v_mfma_f32_32x32x16_bf16 v[80:95], v[202:205], v[136:139], v[80:95]
	v_mfma_f32_32x32x16_bf16 v[64:79], v[210:213], v[136:139], v[64:79]
	ds_read_b128 v[214:217], v194 offset:13312
	ds_read_b128 v[218:221], v194 offset:13344
	ds_read_b128 v[222:225], v194 offset:19968
	ds_read_b128 v[226:229], v194 offset:20000
	ds_read_b128 v[230:233], v194 offset:13376
	ds_read_b128 v[234:237], v194 offset:13408
	ds_read_b128 v[238:241], v194 offset:20032
	ds_read_b128 v[242:245], v194 offset:20064
	s_cbranch_scc1 .LBB0_1497
	v_add_u32_e32 v195, s71, v180
	v_subrev_u32_e32 v198, 31, v195
	v_subrev_u32_e32 v197, 63, v195
	v_cmp_le_i32_e32 vcc, v198, v189
	s_nop 6
	v_cndmask_b32_e32 v64, v177, v64, vcc
	v_cmp_lt_i32_e32 vcc, v197, v189
	s_nop 1
	v_cndmask_b32_e32 v81, v177, v81, vcc
	v_cmp_le_i32_e32 vcc, v197, v189
	v_subrev_u32_e32 v197, 30, v195
	s_nop 0
	v_cndmask_b32_e32 v80, v177, v80, vcc
	v_cmp_le_i32_e32 vcc, v197, v189
	v_subrev_u32_e32 v197, 61, v195
	s_nop 0
	v_cndmask_b32_e32 v65, v177, v65, vcc
	v_cmp_le_i32_e32 vcc, v197, v189
	v_subrev_u32_e32 v197, 29, v195
	s_nop 0
	v_cndmask_b32_e32 v82, v177, v82, vcc
	v_cmp_le_i32_e32 vcc, v197, v189
	v_subrev_u32_e32 v197, 60, v195
	s_nop 0
	v_cndmask_b32_e32 v66, v177, v66, vcc
	v_cmp_le_i32_e32 vcc, v197, v189
	v_subrev_u32_e32 v197, 28, v195
	s_nop 0
	v_cndmask_b32_e32 v83, v177, v83, vcc
	v_cmp_le_i32_e32 vcc, v197, v189
	v_subrev_u32_e32 v197, 55, v195
	s_nop 0
	v_cndmask_b32_e32 v67, v177, v67, vcc
	v_cmp_le_i32_e32 vcc, v197, v189
	v_subrev_u32_e32 v197, 23, v195
	s_nop 0
	v_cndmask_b32_e32 v84, v177, v84, vcc
	v_cmp_le_i32_e32 vcc, v197, v189
	v_subrev_u32_e32 v197, 54, v195
	s_nop 0
	v_cndmask_b32_e32 v68, v177, v68, vcc
	v_cmp_le_i32_e32 vcc, v197, v189
	v_subrev_u32_e32 v197, 22, v195
	s_nop 0
	v_cndmask_b32_e32 v85, v177, v85, vcc
	v_cmp_le_i32_e32 vcc, v197, v189
	v_subrev_u32_e32 v197, 53, v195
	s_nop 0
	v_cndmask_b32_e32 v69, v177, v69, vcc
	v_cmp_le_i32_e32 vcc, v197, v189
	v_subrev_u32_e32 v197, 21, v195
	s_nop 0
	v_cndmask_b32_e32 v86, v177, v86, vcc
	v_cmp_le_i32_e32 vcc, v197, v189
	v_subrev_u32_e32 v197, 52, v195
	s_nop 0
	v_cndmask_b32_e32 v70, v177, v70, vcc
	v_cmp_le_i32_e32 vcc, v197, v189
	v_subrev_u32_e32 v197, 20, v195
	s_nop 0
	v_cndmask_b32_e32 v87, v177, v87, vcc
	v_cmp_le_i32_e32 vcc, v197, v189
	v_subrev_u32_e32 v197, 47, v195
	s_nop 0
	v_cndmask_b32_e32 v71, v177, v71, vcc
	v_cmp_le_i32_e32 vcc, v197, v189
	v_add_u32_e32 v197, -15, v195
	s_nop 0
	v_cndmask_b32_e32 v88, v177, v88, vcc
	v_cmp_le_i32_e32 vcc, v197, v189
	v_subrev_u32_e32 v197, 46, v195
	s_nop 0
	v_cndmask_b32_e32 v72, v177, v72, vcc
	v_cmp_le_i32_e32 vcc, v197, v189
	v_add_u32_e32 v197, -14, v195
	s_nop 0
	v_cndmask_b32_e32 v89, v177, v89, vcc
	v_cmp_le_i32_e32 vcc, v197, v189
	v_subrev_u32_e32 v197, 45, v195
	s_nop 0
	v_cndmask_b32_e32 v73, v177, v73, vcc
	v_cmp_le_i32_e32 vcc, v197, v189
	v_add_u32_e32 v197, -13, v195
	s_nop 0
	v_cndmask_b32_e32 v90, v177, v90, vcc
	v_cmp_le_i32_e32 vcc, v197, v189
	v_subrev_u32_e32 v197, 44, v195
	s_nop 0
	v_cndmask_b32_e32 v74, v177, v74, vcc
	v_cmp_le_i32_e32 vcc, v197, v189
	v_add_u32_e32 v197, -12, v195
	s_nop 0
	v_cndmask_b32_e32 v91, v177, v91, vcc
	v_cmp_le_i32_e32 vcc, v197, v189
	v_subrev_u32_e32 v197, 39, v195
	s_nop 0
	v_cndmask_b32_e32 v75, v177, v75, vcc
	v_cmp_le_i32_e32 vcc, v197, v189
	v_add_u32_e32 v197, -7, v195
	s_nop 0
	v_cndmask_b32_e32 v92, v177, v92, vcc
	v_cmp_le_i32_e32 vcc, v197, v189
	v_subrev_u32_e32 v197, 38, v195
	s_nop 0
	v_cndmask_b32_e32 v76, v177, v76, vcc
	v_cmp_le_i32_e32 vcc, v197, v189
	v_add_u32_e32 v197, -6, v195
	s_nop 0
	v_cndmask_b32_e32 v93, v177, v93, vcc
	v_cmp_le_i32_e32 vcc, v197, v189
	v_subrev_u32_e32 v197, 37, v195
	s_nop 0
	v_cndmask_b32_e32 v77, v177, v77, vcc
	v_cmp_le_i32_e32 vcc, v197, v189
	v_add_u32_e32 v197, -5, v195
	s_nop 0
	v_cndmask_b32_e32 v94, v177, v94, vcc
	v_cmp_le_i32_e32 vcc, v197, v189
	v_subrev_u32_e32 v197, 36, v195
	v_add_u32_e32 v195, -4, v195
	v_cndmask_b32_e32 v78, v177, v78, vcc
	v_cmp_le_i32_e32 vcc, v197, v189
	s_nop 1
	v_cndmask_b32_e32 v95, v177, v95, vcc
	v_cmp_le_i32_e32 vcc, v195, v189
	s_nop 1
	v_cndmask_b32_e32 v79, v177, v79, vcc

; #define LAS __attribute__((address_space(3)))
; #define MFMA32(a, b, c) __builtin_amdgcn_mfma_f32_32x32x16_bf16((a), (b), (c), 0, 0, 0)
; template <int DQK, int DV, bool CAUSAL, int KT, bool PRIO>
; DI void attn_unit(const bf16_t* Qb, int qpitch, const bf16_t* Kb, int kpitch, const bf16_t* Vtb, int vpitch, bf16_t* Ob, int opitch, int q0, int nt, LAS unsigned char* lds, float kbound, const float* qgain, const int* qpos, float qscale) {
;     ...
;                     f32x16 s0 = negm, s1 = negm;
;                     const LAS unsigned char* kb = lds + buf * KBUF + (64 * hf + r) * KS + h * 16;
;                     const LAS unsigned char* vb = lds + VOFF + buf * VBUF + r * VS + h * 8 + 128 * hf;
;                     bf16x8 kf0[KSN], kf1[KSN], vf[4][NDB];
; #pragma unroll
;                     for (int ks = 0; ks < KSN; ++ks) { kf0[ks] = *(const LAS bf16x8*)(kb + ks * 32); kf1[ks] = *(const LAS bf16x8*)(kb + 32 * KS + ks * 32); }
;                     __builtin_amdgcn_sched_barrier(0); __builtin_amdgcn_s_setprio(1); __builtin_amdgcn_sched_barrier(0);
; #pragma unroll
;                     for (int ks = 0; ks < KSN; ++ks) { s0 = MFMA32(kf0[ks], qf[ks], s0); s1 = MFMA32(kf1[ks], qf[ks], s1); }
;                     __builtin_amdgcn_sched_barrier(0); __builtin_amdgcn_s_setprio(0); __builtin_amdgcn_sched_barrier(0);
; #pragma unroll
;                     for (int q4 = 0; q4 < 4; ++q4)
; #pragma unroll
;                         for (int d = 0; d < NDB; ++d) { const LAS unsigned char* vp = vb + d * 32 * VS + q4 * 32;
;                             const s16x4 lo = *(const LAS s16x4*)vp, hi = *(const LAS s16x4*)(vp + 16); vf[q4][d] = (bf16x8){lo[0], lo[1], lo[2], lo[3], hi[0], hi[1], hi[2], hi[3]}; }
;                     if (CAUSAL && key0 + 63 > qlo) {
; #pragma unroll
;                         for (int i = 0; i < 16; ++i) { const int key = key0 + (i & 3) + 8 * (i >> 2) + 4 * h; if (key > qabs) s0[i] = -1e30f; if (key + 32 > qabs) s1[i] = -1e30f; }
.LBB0_1505:
	ds_read_b128 v[198:201], v194 offset:13440
	ds_read_b128 v[202:205], v194 offset:13472
	ds_read_b128 v[206:209], v194 offset:20096
	ds_read_b128 v[210:213], v194 offset:20128
	s_setprio 1
	s_setprio 0
	s_waitcnt lgkmcnt(4)
	v_mfma_f32_32x32x16_bf16 v[80:95], v[214:217], v[116:119], v[48:63]
	s_add_i32 s12, s71, 64
	s_cmp_le_i32 s12, s69
	v_mfma_f32_32x32x16_bf16 v[64:79], v[222:225], v[116:119], v[48:63]
	v_mfma_f32_32x32x16_bf16 v[80:95], v[218:221], v[120:123], v[80:95]
	v_mfma_f32_32x32x16_bf16 v[64:79], v[226:229], v[120:123], v[64:79]
	v_mfma_f32_32x32x16_bf16 v[80:95], v[230:233], v[124:127], v[80:95]
	v_mfma_f32_32x32x16_bf16 v[64:79], v[238:241], v[124:127], v[64:79]
	v_mfma_f32_32x32x16_bf16 v[80:95], v[234:237], v[128:131], v[80:95]
	v_mfma_f32_32x32x16_bf16 v[64:79], v[242:245], v[128:131], v[64:79]
	ds_read2_b64 v[156:159], v14 offset0:16 offset1:18
	ds_read2_b64 v[140:143], v14 offset0:20 offset1:22
	ds_read2_b64 v[152:155], v15 offset0:48 offset1:50
	ds_read2_b64 v[148:151], v15 offset0:52 offset1:54
	ds_read2_b64 v[144:147], v14 offset0:24 offset1:26
	ds_read2_b64 v[10:13], v15 offset0:56 offset1:58
	ds_read2_b64 v[6:9], v14 offset0:28 offset1:30
	ds_read2_b64 v[2:5], v15 offset0:60 offset1:62
	s_waitcnt lgkmcnt(8)
	v_mfma_f32_32x32x16_bf16 v[80:95], v[198:201], v[132:135], v[80:95]
	v_mfma_f32_32x32x16_bf16 v[64:79], v[206:209], v[132:135], v[64:79]
	v_mfma_f32_32x32x16_bf16 v[80:95], v[202:205], v[136:139], v[80:95]
	v_mfma_f32_32x32x16_bf16 v[64:79], v[210:213], v[136:139], v[64:79]
	s_cbranch_scc1 .LBB0_1507
	v_add_u32_e32 v14, s71, v180
	v_add_u32_e32 v194, 33, v14
	v_add_u32_e32 v15, 1, v14
	v_cmp_le_i32_e32 vcc, v194, v189
	s_nop 6
	v_cndmask_b32_e32 v64, v177, v64, vcc
	v_cmp_lt_i32_e32 vcc, v15, v189
	s_nop 1
	v_cndmask_b32_e32 v81, v177, v81, vcc
	v_cmp_le_i32_e32 vcc, v15, v189
	v_add_u32_e32 v15, 34, v14
	s_nop 0
	v_cndmask_b32_e32 v80, v177, v80, vcc
	v_cmp_le_i32_e32 vcc, v15, v189
	v_add_u32_e32 v15, 3, v14
	s_nop 0
	v_cndmask_b32_e32 v65, v177, v65, vcc
	v_cmp_le_i32_e32 vcc, v15, v189
	v_add_u32_e32 v15, 35, v14
	s_nop 0
	v_cndmask_b32_e32 v82, v177, v82, vcc
	v_cmp_le_i32_e32 vcc, v15, v189
	v_add_u32_e32 v15, 4, v14
	s_nop 0
	v_cndmask_b32_e32 v66, v177, v66, vcc
	v_cmp_le_i32_e32 vcc, v15, v189
	v_add_u32_e32 v15, 36, v14
	s_nop 0
	v_cndmask_b32_e32 v83, v177, v83, vcc
	v_cmp_le_i32_e32 vcc, v15, v189
	v_add_u32_e32 v15, 9, v14
	s_nop 0
	v_cndmask_b32_e32 v67, v177, v67, vcc
	v_cmp_le_i32_e32 vcc, v15, v189
	v_add_u32_e32 v15, 41, v14
	s_nop 0
	v_cndmask_b32_e32 v84, v177, v84, vcc
	v_cmp_le_i32_e32 vcc, v15, v189
	v_add_u32_e32 v15, 10, v14
	s_nop 0
	v_cndmask_b32_e32 v68, v177, v68, vcc
	v_cmp_le_i32_e32 vcc, v15, v189
	v_add_u32_e32 v15, 42, v14
	s_nop 0
	v_cndmask_b32_e32 v85, v177, v85, vcc
	v_cmp_le_i32_e32 vcc, v15, v189
	v_add_u32_e32 v15, 11, v14
	s_nop 0
	v_cndmask_b32_e32 v69, v177, v69, vcc
	v_cmp_le_i32_e32 vcc, v15, v189
	v_add_u32_e32 v15, 43, v14
	s_nop 0
	v_cndmask_b32_e32 v86, v177, v86, vcc
	v_cmp_le_i32_e32 vcc, v15, v189
	v_add_u32_e32 v15, 12, v14
	s_nop 0
	v_cndmask_b32_e32 v70, v177, v70, vcc
	v_cmp_le_i32_e32 vcc, v15, v189
	v_add_u32_e32 v15, 44, v14
	s_nop 0
	v_cndmask_b32_e32 v87, v177, v87, vcc
	v_cmp_le_i32_e32 vcc, v15, v189
	v_add_u32_e32 v15, 17, v14
	s_nop 0
	v_cndmask_b32_e32 v71, v177, v71, vcc
	v_cmp_le_i32_e32 vcc, v15, v189
	v_add_u32_e32 v15, 49, v14
	s_nop 0
	v_cndmask_b32_e32 v88, v177, v88, vcc
	v_cmp_le_i32_e32 vcc, v15, v189
	v_add_u32_e32 v15, 18, v14
	s_nop 0
	v_cndmask_b32_e32 v72, v177, v72, vcc
	v_cmp_le_i32_e32 vcc, v15, v189
	v_add_u32_e32 v15, 50, v14
	s_nop 0
	v_cndmask_b32_e32 v89, v177, v89, vcc
	v_cmp_le_i32_e32 vcc, v15, v189
	v_add_u32_e32 v15, 19, v14
	s_nop 0
	v_cndmask_b32_e32 v73, v177, v73, vcc
	v_cmp_le_i32_e32 vcc, v15, v189
	v_add_u32_e32 v15, 51, v14
	s_nop 0
	v_cndmask_b32_e32 v90, v177, v90, vcc
	v_cmp_le_i32_e32 vcc, v15, v189
	v_add_u32_e32 v15, 20, v14
	s_nop 0
	v_cndmask_b32_e32 v74, v177, v74, vcc
	v_cmp_le_i32_e32 vcc, v15, v189
	v_add_u32_e32 v15, 52, v14
	s_nop 0
	v_cndmask_b32_e32 v91, v177, v91, vcc
	v_cmp_le_i32_e32 vcc, v15, v189
	v_add_u32_e32 v15, 25, v14
	s_nop 0
	v_cndmask_b32_e32 v75, v177, v75, vcc
	v_cmp_le_i32_e32 vcc, v15, v189
	v_add_u32_e32 v15, 57, v14
	s_nop 0
	v_cndmask_b32_e32 v92, v177, v92, vcc
	v_cmp_le_i32_e32 vcc, v15, v189
	v_add_u32_e32 v15, 26, v14
	s_nop 0
	v_cndmask_b32_e32 v76, v177, v76, vcc
	v_cmp_le_i32_e32 vcc, v15, v189
	v_add_u32_e32 v15, 58, v14
	s_nop 0
	v_cndmask_b32_e32 v93, v177, v93, vcc
	v_cmp_le_i32_e32 vcc, v15, v189
	v_add_u32_e32 v15, 27, v14
	s_nop 0
	v_cndmask_b32_e32 v77, v177, v77, vcc
	v_cmp_le_i32_e32 vcc, v15, v189
	v_add_u32_e32 v15, 59, v14
	s_nop 0
	v_cndmask_b32_e32 v94, v177, v94, vcc
	v_cmp_le_i32_e32 vcc, v15, v189
	v_add_u32_e32 v15, 28, v14
	v_add_u32_e32 v14, 60, v14
	v_cndmask_b32_e32 v78, v177, v78, vcc
	v_cmp_le_i32_e32 vcc, v15, v189
	s_nop 1
	v_cndmask_b32_e32 v95, v177, v95, vcc
	v_cmp_le_i32_e32 vcc, v14, v189
	s_nop 1
	v_cndmask_b32_e32 v79, v177, v79, vcc
